# scan loops: packed fp32 VOP3P ops split into scalar pairs (bit-identical); MoBA item setup: gate-score and Q loads issued together
# baseline (speedup 1.0000x reference)
.LBB0_540:
	s_or_b64 exec, exec, s[8:9]
	s_waitcnt lgkmcnt(0)
	s_barrier
	ds_read_b32 v0, v185
	s_mov_b64 s[8:9], -1
	s_waitcnt lgkmcnt(0)
	v_readfirstlane_b32 s15, v0
	s_cmpk_gt_i32 s15, 0x7ff
	s_cbranch_scc1 .LBB0_535
	s_lshl_b32 s0, s15, 2
	v_mov_b32_e32 v12, v182
	s_andn2_b32 s0, s0, 63
	s_lshl_b32 s2, s15, 11
	s_sub_i32 s0, 0x1fc0, s0
	s_and_b32 s14, s2, 0x6000
	v_lshlrev_b32_e32 v0, 3, v12
	v_ashrrev_i32_e32 v60, 3, v12
	s_add_i32 s38, s14, s0
	v_and_b32_e32 v0, 56, v0
	v_ashrrev_i32_e32 v61, 31, v60
	v_lshlrev_b32_e32 v112, 1, v0
	v_lshl_add_u64 v[0:1], s[38:39], 0, v[60:61]
	v_mov_b64_e32 v[4:5], s[30:31]
	s_and_b32 s17, s15, 3
	v_mad_u64_u32 v[2:3], s[8:9], v0, s63, v[4:5]
	v_mad_i32_i24 v3, v1, s63, v3
	s_lshl_b32 s8, s17, 7
	s_mov_b32 s9, s39
	v_lshl_add_u64 v[0:1], v[2:3], 0, s[8:9]
	v_lshl_add_u64 v[0:1], v[0:1], 0, v[112:113]
	s_movk_i32 s1, 0x1000
	v_add_co_u32_e32 v0, vcc, s1, v0
	s_nop 1
	v_addc_co_u32_e32 v1, vcc, 0, v1, vcc
	s_barrier
	global_load_dwordx4 v[136:139], v[0:1], off offset:1024
	s_movk_i32 s22, 0x90
	v_mad_u64_u32 v[6:7], s[10:11], v60, s22, v[112:113]
	v_add_u32_e32 v0, 0x100, v12
	v_ashrrev_i32_e32 v62, 3, v0
	v_ashrrev_i32_e32 v63, 31, v62
	v_lshl_add_u64 v[0:1], s[38:39], 0, v[62:63]
	v_mad_u64_u32 v[2:3], s[10:11], v0, s63, v[4:5]
	v_mad_i32_i24 v3, v1, s63, v3
	v_lshl_add_u64 v[0:1], v[2:3], 0, s[8:9]
	v_lshl_add_u64 v[0:1], v[0:1], 0, v[112:113]
	v_add_co_u32_e32 v0, vcc, 0x1000, v0
	v_mad_u64_u32 v[4:5], s[10:11], v62, s22, v[112:113]
	s_nop 0
	v_addc_co_u32_e32 v1, vcc, 0, v1, vcc
	global_load_dwordx4 v[0:3], v[0:1], off offset:1024
	v_cmp_eq_u32_e32 vcc, 0, v12
	s_waitcnt vmcnt(0)
	ds_write_b128 v6, v[136:139] offset:36864
	ds_write_b128 v4, v[0:3] offset:36864
	s_and_saveexec_b64 s[10:11], vcc
	ds_write_b32 v193, v113
	s_or_b64 exec, exec, s[10:11]
	s_movk_i32 s2, 0x800
	s_lshr_b32 s21, s0, 8
	v_cmp_gt_i32_e32 vcc, s2, v12
	s_and_saveexec_b64 s[10:11], vcc
	s_movk_i32 s1, 0x84
	s_cbranch_execz .LBB0_548
	s_lshl_b64 s[12:13], s[38:39], 9
	v_readlane_b32 s2, v251, 30
	v_readlane_b32 s3, v251, 31
	s_add_u32 s2, s2, s12
	s_addc_u32 s3, s3, s13
	s_add_u32 s8, s2, s8
	v_and_b32_e32 v0, 31, v12
	s_addc_u32 s9, s3, 0
	v_cmp_gt_u32_e32 vcc, s21, v0
	v_lshlrev_b32_e32 v0, 2, v0
	v_mov_b32_e32 v1, v113
	v_lshl_add_u64 v[2:3], s[8:9], 0, v[0:1]
	s_mov_b64 s[12:13], 0
	v_mov_b32_e32 v1, v12
	s_and_saveexec_b64 s[8:9], vcc
	s_cbranch_execz .Lmg_skip
	v_ashrrev_i32_e32 v4, 5, v12
	v_ashrrev_i32_e32 v5, 31, v4
	v_lshlrev_b64 v[6:7], 9, v[4:5]
	v_lshl_add_u64 v[6:7], v[2:3], 0, v[6:7]
	s_mov_b64 s[12:13], 0x1000
	global_load_dword v136, v[6:7], off
	v_lshl_add_u64 v[6:7], v[6:7], 0, s[12:13]
	global_load_dword v137, v[6:7], off
	v_lshl_add_u64 v[6:7], v[6:7], 0, s[12:13]
	global_load_dword v138, v[6:7], off
	v_lshl_add_u64 v[6:7], v[6:7], 0, s[12:13]
	global_load_dword v139, v[6:7], off
	v_lshl_add_u64 v[6:7], v[6:7], 0, s[12:13]
	global_load_dword v140, v[6:7], off
	v_lshl_add_u64 v[6:7], v[6:7], 0, s[12:13]
	global_load_dword v141, v[6:7], off
	v_lshl_add_u64 v[6:7], v[6:7], 0, s[12:13]
	global_load_dword v142, v[6:7], off
	v_lshl_add_u64 v[6:7], v[6:7], 0, s[12:13]
	global_load_dword v143, v[6:7], off
	v_mul_u32_u24_e32 v4, 0x84, v4
	v_add_u32_e32 v4, v4, v0
	v_add_u32_e32 v4, 0xf800, v4
	s_waitcnt vmcnt(0)
	ds_write_b32 v4, v136
	ds_write_b32 v4, v137 offset:1056
	ds_write_b32 v4, v138 offset:2112
	ds_write_b32 v4, v139 offset:3168
	ds_write_b32 v4, v140 offset:4224
	ds_write_b32 v4, v141 offset:5280
	ds_write_b32 v4, v142 offset:6336
	ds_write_b32 v4, v143 offset:7392
.Lmg_skip:
	s_or_b64 exec, exec, s[8:9]
.LBB0_548:
	s_or_b64 exec, exec, s[10:11]
	s_and_b32 s16, s15, 15
	s_lshl_b32 s15, s17, 6
	v_cmp_gt_i32_e32 vcc, 64, v12
	s_waitcnt lgkmcnt(0)
	s_barrier
	s_and_saveexec_b64 s[12:13], vcc
	s_cbranch_execz .LBB0_563
	s_cmpk_gt_u32 s0, 0xff
	s_cselect_b64 s[10:11], -1, 0
	s_max_u32 s17, s21, 1
	v_mul_lo_u32 v3, v12, s1
	s_cmpk_lt_u32 s0, 0x100
	v_mov_b32_e32 v1, -1
	v_add_u32_e32 v0, 0xf800, v3
	s_cbranch_scc1 .LBB0_552
	v_add_u32_e32 v2, 0xf800, v3
	s_mov_b32 s8, 0
	v_mov_b32_e32 v1, -1
	v_mov_b32_e32 v4, 0xff800000
